# MFMA order: each accumulator's two K-half MFMAs issued back-to-back (accumulator forwarding) in the 4 big GEMM loops
# speedup vs baseline: 1.0077x; 1.0066x over previous
.LBB0_139:
	s_add_u32 s22, s18, 0xfff00080
	s_addc_u32 s23, s19, -1
	s_add_i32 s49, 0, 0x10000
	s_cmp_eq_u32 s48, 60
	s_cselect_b32 s25, s9, s23
	s_cselect_b32 s24, s44, s22
	s_cselect_b32 s23, s7, s47
	s_cselect_b32 s22, s45, s46
	s_add_i32 s52, 0, 0x14000
	v_add_u32_e32 v156, s49, v145
	v_add_u32_e32 v172, s52, v145
	ds_read_b128 v[140:143], v156
	ds_read_b128 v[148:151], v156 offset:1024
	ds_read_b128 v[152:155], v156 offset:2048
	ds_read_b128 v[156:159], v156 offset:3072
	ds_read_b128 v[160:163], v172
	ds_read_b128 v[164:167], v172 offset:1024
	ds_read_b128 v[168:171], v172 offset:2048
	ds_read_b128 v[190:193], v172 offset:3072
	v_lshl_add_u64 v[172:173], s[18:19], 0, v[136:137]
	s_add_i32 m0, s31, 0xc000
	ds_read_b128 v[194:197], v147
	ds_read_b128 v[198:201], v147 offset:1024
	ds_read_b128 v[202:205], v147 offset:2048
	ds_read_b128 v[206:209], v147 offset:3072
	ds_read_b128 v[228:231], v147 offset:4096
	ds_read_b128 v[232:235], v147 offset:5120
	ds_read_b128 v[236:239], v147 offset:6144
	ds_read_b128 v[240:243], v147 offset:7168
	global_load_lds_dwordx4 v[172:173], off
	v_lshl_add_u64 v[172:173], s[18:19], 0, v[138:139]
	s_add_i32 m0, s31, 0xe000
	s_nop 0
	global_load_lds_dwordx4 v[172:173], off
	s_waitcnt vmcnt(8)
	s_waitcnt lgkmcnt(0)
	s_barrier
	s_setprio 1
	s_waitcnt lgkmcnt(0)
	v_mfma_f32_16x16x32_bf16 v[126:129], v[140:143], v[194:197], v[126:129]
	v_mfma_f32_16x16x32_bf16 v[126:129], v[148:151], v[198:201], v[126:129]
	v_mfma_f32_16x16x32_bf16 v[122:125], v[152:155], v[194:197], v[122:125]
	v_mfma_f32_16x16x32_bf16 v[122:125], v[156:159], v[198:201], v[122:125]
	v_mfma_f32_16x16x32_bf16 v[118:121], v[140:143], v[202:205], v[118:121]
	v_mfma_f32_16x16x32_bf16 v[118:121], v[148:151], v[206:209], v[118:121]
	v_mfma_f32_16x16x32_bf16 v[110:113], v[152:155], v[202:205], v[110:113]
	v_mfma_f32_16x16x32_bf16 v[110:113], v[156:159], v[206:209], v[110:113]
	v_mfma_f32_16x16x32_bf16 v[102:105], v[140:143], v[228:231], v[102:105]
	v_mfma_f32_16x16x32_bf16 v[102:105], v[148:151], v[232:235], v[102:105]
	v_mfma_f32_16x16x32_bf16 v[94:97], v[152:155], v[228:231], v[94:97]
	v_mfma_f32_16x16x32_bf16 v[94:97], v[156:159], v[232:235], v[94:97]
	v_mfma_f32_16x16x32_bf16 v[86:89], v[140:143], v[236:239], v[86:89]
	v_mfma_f32_16x16x32_bf16 v[86:89], v[148:151], v[240:243], v[86:89]
	v_mfma_f32_16x16x32_bf16 v[78:81], v[152:155], v[236:239], v[78:81]
	v_mfma_f32_16x16x32_bf16 v[78:81], v[156:159], v[240:243], v[78:81]
	s_setprio 0
	s_setprio 1
	v_mfma_f32_16x16x32_bf16 v[114:117], v[160:163], v[194:197], v[114:117]
	v_mfma_f32_16x16x32_bf16 v[114:117], v[164:167], v[198:201], v[114:117]
	v_mfma_f32_16x16x32_bf16 v[106:109], v[168:171], v[194:197], v[106:109]
	v_mfma_f32_16x16x32_bf16 v[106:109], v[190:193], v[198:201], v[106:109]
	v_mfma_f32_16x16x32_bf16 v[98:101], v[160:163], v[202:205], v[98:101]
	v_mfma_f32_16x16x32_bf16 v[98:101], v[164:167], v[206:209], v[98:101]
	v_mfma_f32_16x16x32_bf16 v[90:93], v[168:171], v[202:205], v[90:93]
	v_mfma_f32_16x16x32_bf16 v[90:93], v[190:193], v[206:209], v[90:93]
	v_mfma_f32_16x16x32_bf16 v[82:85], v[160:163], v[228:231], v[82:85]
	v_mfma_f32_16x16x32_bf16 v[82:85], v[164:167], v[232:235], v[82:85]
	v_mfma_f32_16x16x32_bf16 v[74:77], v[168:171], v[228:231], v[74:77]
	v_mfma_f32_16x16x32_bf16 v[74:77], v[190:193], v[232:235], v[74:77]
	v_mfma_f32_16x16x32_bf16 v[70:73], v[160:163], v[236:239], v[70:73]
	v_mfma_f32_16x16x32_bf16 v[70:73], v[164:167], v[240:243], v[70:73]
	v_mfma_f32_16x16x32_bf16 v[66:69], v[168:171], v[236:239], v[66:69]
	v_mfma_f32_16x16x32_bf16 v[66:69], v[190:193], v[240:243], v[66:69]
	s_setprio 0
	s_barrier
	s_add_i32 s49, s49, s26
	v_lshl_add_u64 v[172:173], s[22:23], 0, v[0:1]
	s_mov_b32 m0, s49
	ds_read_b128 v[194:197], v147 offset:16384
	ds_read_b128 v[198:201], v147 offset:17408
	ds_read_b128 v[202:205], v147 offset:18432
	ds_read_b128 v[206:209], v147 offset:19456
	ds_read_b128 v[228:231], v147 offset:20480
	ds_read_b128 v[232:235], v147 offset:21504
	ds_read_b128 v[236:239], v147 offset:22528
	ds_read_b128 v[240:243], v147 offset:23552
	global_load_lds_dwordx4 v[172:173], off
	s_add_i32 m0, s49, 0x2000
	s_add_u32 s50, s22, 0x100000
	v_lshl_add_u64 v[178:179], s[22:23], 0, v[130:131]
	s_addc_u32 s51, s23, 0
	s_add_i32 s49, s52, s26
	global_load_lds_dwordx4 v[178:179], off
	v_lshl_add_u64 v[180:181], s[50:51], 0, v[0:1]
	s_mov_b32 m0, s49
	v_lshl_add_u64 v[210:211], s[24:25], 0, v[132:133]
	global_load_lds_dwordx4 v[180:181], off
	v_lshl_add_u64 v[180:181], s[50:51], 0, v[130:131]
	s_add_i32 m0, s49, 0x2000
	s_nop 0
	global_load_lds_dwordx4 v[180:181], off
	v_lshl_add_u64 v[180:181], s[24:25], 0, v[134:135]
	s_mov_b32 m0, s31
	s_nop 0
	global_load_lds_dwordx4 v[180:181], off
	s_mov_b32 m0, s36
	s_nop 0
	global_load_lds_dwordx4 v[210:211], off
	s_waitcnt vmcnt(8)
	s_waitcnt lgkmcnt(0)
	s_barrier
	s_setprio 1
	s_waitcnt lgkmcnt(0)
	v_mfma_f32_16x16x32_bf16 v[62:65], v[140:143], v[194:197], v[62:65]
	v_mfma_f32_16x16x32_bf16 v[62:65], v[148:151], v[198:201], v[62:65]
	v_mfma_f32_16x16x32_bf16 v[58:61], v[152:155], v[194:197], v[58:61]
	v_mfma_f32_16x16x32_bf16 v[58:61], v[156:159], v[198:201], v[58:61]
	v_mfma_f32_16x16x32_bf16 v[54:57], v[140:143], v[202:205], v[54:57]
	v_mfma_f32_16x16x32_bf16 v[54:57], v[148:151], v[206:209], v[54:57]
	v_mfma_f32_16x16x32_bf16 v[46:49], v[152:155], v[202:205], v[46:49]
	v_mfma_f32_16x16x32_bf16 v[46:49], v[156:159], v[206:209], v[46:49]
	v_mfma_f32_16x16x32_bf16 v[38:41], v[140:143], v[228:231], v[38:41]
	v_mfma_f32_16x16x32_bf16 v[38:41], v[148:151], v[232:235], v[38:41]
	v_mfma_f32_16x16x32_bf16 v[30:33], v[152:155], v[228:231], v[30:33]
	v_mfma_f32_16x16x32_bf16 v[30:33], v[156:159], v[232:235], v[30:33]
	v_mfma_f32_16x16x32_bf16 v[22:25], v[140:143], v[236:239], v[22:25]
	v_mfma_f32_16x16x32_bf16 v[22:25], v[148:151], v[240:243], v[22:25]
	v_mfma_f32_16x16x32_bf16 v[14:17], v[152:155], v[236:239], v[14:17]
	v_mfma_f32_16x16x32_bf16 v[14:17], v[156:159], v[240:243], v[14:17]
	s_setprio 0
	s_setprio 1
	v_mfma_f32_16x16x32_bf16 v[50:53], v[160:163], v[194:197], v[50:53]
	v_mfma_f32_16x16x32_bf16 v[50:53], v[164:167], v[198:201], v[50:53]
	v_mfma_f32_16x16x32_bf16 v[42:45], v[168:171], v[194:197], v[42:45]
	v_mfma_f32_16x16x32_bf16 v[42:45], v[190:193], v[198:201], v[42:45]
	v_mfma_f32_16x16x32_bf16 v[34:37], v[160:163], v[202:205], v[34:37]
	v_mfma_f32_16x16x32_bf16 v[34:37], v[164:167], v[206:209], v[34:37]
	v_mfma_f32_16x16x32_bf16 v[26:29], v[168:171], v[202:205], v[26:29]
	v_mfma_f32_16x16x32_bf16 v[26:29], v[190:193], v[206:209], v[26:29]
	v_mfma_f32_16x16x32_bf16 v[18:21], v[160:163], v[228:231], v[18:21]
	v_mfma_f32_16x16x32_bf16 v[18:21], v[164:167], v[232:235], v[18:21]
	v_mfma_f32_16x16x32_bf16 v[10:13], v[168:171], v[228:231], v[10:13]
	v_mfma_f32_16x16x32_bf16 v[10:13], v[190:193], v[232:235], v[10:13]
	v_mfma_f32_16x16x32_bf16 v[6:9], v[160:163], v[236:239], v[6:9]
	v_mfma_f32_16x16x32_bf16 v[6:9], v[164:167], v[240:243], v[6:9]
	v_mfma_f32_16x16x32_bf16 v[2:5], v[168:171], v[236:239], v[2:5]
	v_mfma_f32_16x16x32_bf16 v[2:5], v[190:193], v[240:243], v[2:5]
	s_setprio 0
	s_barrier
	s_add_i32 s49, 0, 0x18000
	s_add_i32 s50, 0, 0x1c000
	v_add_u32_e32 v156, s49, v145
	v_add_u32_e32 v175, s50, v145
	ds_read_b128 v[140:143], v156
	ds_read_b128 v[148:151], v156 offset:1024
	ds_read_b128 v[152:155], v156 offset:2048
	ds_read_b128 v[156:159], v156 offset:3072
	ds_read_b128 v[160:163], v175
	ds_read_b128 v[164:167], v175 offset:1024
	ds_read_b128 v[168:171], v175 offset:2048
	ds_read_b128 v[190:193], v175 offset:3072
	s_add_u32 s24, s24, 0x100000
	s_addc_u32 s25, s25, 0
	s_mov_b32 m0, s37
	v_lshl_add_u64 v[244:245], s[24:25], 0, v[134:135]
	ds_read_b128 v[194:197], v147 offset:32768
	ds_read_b128 v[198:201], v147 offset:33792
	ds_read_b128 v[202:205], v147 offset:34816
	ds_read_b128 v[206:209], v147 offset:35840
	ds_read_b128 v[228:231], v147 offset:36864
	ds_read_b128 v[232:235], v147 offset:37888
	ds_read_b128 v[236:239], v147 offset:38912
	ds_read_b128 v[240:243], v147 offset:39936
	global_load_lds_dwordx4 v[244:245], off
	v_lshl_add_u64 v[244:245], s[24:25], 0, v[132:133]
	s_mov_b32 m0, s38
	s_nop 0
	global_load_lds_dwordx4 v[244:245], off
	s_waitcnt vmcnt(8)
	s_waitcnt lgkmcnt(0)
	s_barrier
	s_setprio 1
	s_waitcnt lgkmcnt(0)
	v_mfma_f32_16x16x32_bf16 v[126:129], v[140:143], v[194:197], v[126:129]
	v_mfma_f32_16x16x32_bf16 v[126:129], v[148:151], v[198:201], v[126:129]
	v_mfma_f32_16x16x32_bf16 v[122:125], v[152:155], v[194:197], v[122:125]
	v_mfma_f32_16x16x32_bf16 v[122:125], v[156:159], v[198:201], v[122:125]
	v_mfma_f32_16x16x32_bf16 v[118:121], v[140:143], v[202:205], v[118:121]
	v_mfma_f32_16x16x32_bf16 v[118:121], v[148:151], v[206:209], v[118:121]
	v_mfma_f32_16x16x32_bf16 v[110:113], v[152:155], v[202:205], v[110:113]
	v_mfma_f32_16x16x32_bf16 v[110:113], v[156:159], v[206:209], v[110:113]
	v_mfma_f32_16x16x32_bf16 v[102:105], v[140:143], v[228:231], v[102:105]
	v_mfma_f32_16x16x32_bf16 v[102:105], v[148:151], v[232:235], v[102:105]
	v_mfma_f32_16x16x32_bf16 v[94:97], v[152:155], v[228:231], v[94:97]
	v_mfma_f32_16x16x32_bf16 v[94:97], v[156:159], v[232:235], v[94:97]
	v_mfma_f32_16x16x32_bf16 v[86:89], v[140:143], v[236:239], v[86:89]
	v_mfma_f32_16x16x32_bf16 v[86:89], v[148:151], v[240:243], v[86:89]
	v_mfma_f32_16x16x32_bf16 v[78:81], v[152:155], v[236:239], v[78:81]
	v_mfma_f32_16x16x32_bf16 v[78:81], v[156:159], v[240:243], v[78:81]
	s_setprio 0
	s_setprio 1
	v_mfma_f32_16x16x32_bf16 v[114:117], v[160:163], v[194:197], v[114:117]
	v_mfma_f32_16x16x32_bf16 v[114:117], v[164:167], v[198:201], v[114:117]
	v_mfma_f32_16x16x32_bf16 v[106:109], v[168:171], v[194:197], v[106:109]
	v_mfma_f32_16x16x32_bf16 v[106:109], v[190:193], v[198:201], v[106:109]
	v_mfma_f32_16x16x32_bf16 v[98:101], v[160:163], v[202:205], v[98:101]
	v_mfma_f32_16x16x32_bf16 v[98:101], v[164:167], v[206:209], v[98:101]
	v_mfma_f32_16x16x32_bf16 v[90:93], v[168:171], v[202:205], v[90:93]
	v_mfma_f32_16x16x32_bf16 v[90:93], v[190:193], v[206:209], v[90:93]
	v_mfma_f32_16x16x32_bf16 v[82:85], v[160:163], v[228:231], v[82:85]
	v_mfma_f32_16x16x32_bf16 v[82:85], v[164:167], v[232:235], v[82:85]
	v_mfma_f32_16x16x32_bf16 v[74:77], v[168:171], v[228:231], v[74:77]
	v_mfma_f32_16x16x32_bf16 v[74:77], v[190:193], v[232:235], v[74:77]
	v_mfma_f32_16x16x32_bf16 v[70:73], v[160:163], v[236:239], v[70:73]
	v_mfma_f32_16x16x32_bf16 v[70:73], v[164:167], v[240:243], v[70:73]
	v_mfma_f32_16x16x32_bf16 v[66:69], v[168:171], v[236:239], v[66:69]
	v_mfma_f32_16x16x32_bf16 v[66:69], v[190:193], v[240:243], v[66:69]
	s_setprio 0
	s_barrier
	s_add_i32 s24, s49, s26
	v_lshl_add_u64 v[172:173], v[172:173], 0, s[34:35]
	s_mov_b32 m0, s24
	ds_read_b128 v[194:197], v147 offset:49152
	ds_read_b128 v[198:201], v147 offset:50176
	ds_read_b128 v[202:205], v147 offset:51200
	ds_read_b128 v[206:209], v147 offset:52224
	ds_read_b128 v[228:231], v147 offset:53248
	ds_read_b128 v[232:235], v147 offset:54272
	ds_read_b128 v[236:239], v147 offset:55296
	ds_read_b128 v[240:243], v147 offset:56320
	global_load_lds_dwordx4 v[172:173], off
	s_add_i32 m0, s24, 0x2000
	s_add_u32 s22, s22, 0x100080
	v_lshl_add_u64 v[172:173], v[178:179], 0, s[34:35]
	s_addc_u32 s23, s23, 0
	s_add_i32 s24, s50, s26
	global_load_lds_dwordx4 v[172:173], off
	v_lshl_add_u64 v[172:173], s[22:23], 0, v[0:1]
	s_mov_b32 m0, s24
	s_nop 0
	global_load_lds_dwordx4 v[172:173], off
	v_lshl_add_u64 v[172:173], s[22:23], 0, v[130:131]
	s_add_i32 m0, s24, 0x2000
	s_nop 0
	global_load_lds_dwordx4 v[172:173], off
	v_lshl_add_u64 v[172:173], v[180:181], 0, s[34:35]
	s_mov_b32 m0, s39
	s_nop 0
	global_load_lds_dwordx4 v[172:173], off
	v_lshl_add_u64 v[172:173], v[210:211], 0, s[34:35]
	s_mov_b32 m0, s40
	s_nop 0
	global_load_lds_dwordx4 v[172:173], off
	s_waitcnt vmcnt(8)
	s_waitcnt lgkmcnt(0)
	s_barrier
	s_setprio 1
	s_waitcnt lgkmcnt(0)
	v_mfma_f32_16x16x32_bf16 v[62:65], v[140:143], v[194:197], v[62:65]
	v_mfma_f32_16x16x32_bf16 v[62:65], v[148:151], v[198:201], v[62:65]
	v_mfma_f32_16x16x32_bf16 v[58:61], v[152:155], v[194:197], v[58:61]
	v_mfma_f32_16x16x32_bf16 v[58:61], v[156:159], v[198:201], v[58:61]
	v_mfma_f32_16x16x32_bf16 v[54:57], v[140:143], v[202:205], v[54:57]
	v_mfma_f32_16x16x32_bf16 v[54:57], v[148:151], v[206:209], v[54:57]
	v_mfma_f32_16x16x32_bf16 v[46:49], v[152:155], v[202:205], v[46:49]
	v_mfma_f32_16x16x32_bf16 v[46:49], v[156:159], v[206:209], v[46:49]
	v_mfma_f32_16x16x32_bf16 v[38:41], v[140:143], v[228:231], v[38:41]
	v_mfma_f32_16x16x32_bf16 v[38:41], v[148:151], v[232:235], v[38:41]
	v_mfma_f32_16x16x32_bf16 v[30:33], v[152:155], v[228:231], v[30:33]
	v_mfma_f32_16x16x32_bf16 v[30:33], v[156:159], v[232:235], v[30:33]
	v_mfma_f32_16x16x32_bf16 v[22:25], v[140:143], v[236:239], v[22:25]
	v_mfma_f32_16x16x32_bf16 v[22:25], v[148:151], v[240:243], v[22:25]
	v_mfma_f32_16x16x32_bf16 v[14:17], v[152:155], v[236:239], v[14:17]
	v_mfma_f32_16x16x32_bf16 v[14:17], v[156:159], v[240:243], v[14:17]
	s_setprio 0
	s_setprio 1
	v_mfma_f32_16x16x32_bf16 v[50:53], v[160:163], v[194:197], v[50:53]
	v_mfma_f32_16x16x32_bf16 v[50:53], v[164:167], v[198:201], v[50:53]
	v_mfma_f32_16x16x32_bf16 v[42:45], v[168:171], v[194:197], v[42:45]
	v_mfma_f32_16x16x32_bf16 v[42:45], v[190:193], v[198:201], v[42:45]
	v_mfma_f32_16x16x32_bf16 v[34:37], v[160:163], v[202:205], v[34:37]
	v_mfma_f32_16x16x32_bf16 v[34:37], v[164:167], v[206:209], v[34:37]
	v_mfma_f32_16x16x32_bf16 v[26:29], v[168:171], v[202:205], v[26:29]
	v_mfma_f32_16x16x32_bf16 v[26:29], v[190:193], v[206:209], v[26:29]
	v_mfma_f32_16x16x32_bf16 v[18:21], v[160:163], v[228:231], v[18:21]
	v_mfma_f32_16x16x32_bf16 v[18:21], v[164:167], v[232:235], v[18:21]
	v_mfma_f32_16x16x32_bf16 v[10:13], v[168:171], v[228:231], v[10:13]
	v_mfma_f32_16x16x32_bf16 v[10:13], v[190:193], v[232:235], v[10:13]
	v_mfma_f32_16x16x32_bf16 v[6:9], v[160:163], v[236:239], v[6:9]
	v_mfma_f32_16x16x32_bf16 v[6:9], v[164:167], v[240:243], v[6:9]
	v_mfma_f32_16x16x32_bf16 v[2:5], v[168:171], v[236:239], v[2:5]
	v_mfma_f32_16x16x32_bf16 v[2:5], v[190:193], v[240:243], v[2:5]
	s_setprio 0
	s_barrier
	s_add_i32 s48, s48, 2
	s_add_u32 s18, s18, 0x100
	s_addc_u32 s19, s19, 0
	s_add_u32 s46, s46, 0x100
	s_addc_u32 s47, s47, 0
	s_cmp_gt_u32 s48, 61
	s_cbranch_scc0 .LBB0_139
	s_and_b64 vcc, exec, s[4:5]
	s_cbranch_vccz .LBB0_142
	s_barrier

.LBB0_575:
	s_add_u32 s22, s18, 0xfff00080
	s_addc_u32 s23, s19, -1
	s_add_i32 s53, 0, 0x10000
	s_cmp_eq_u32 s52, 60
	s_cselect_b32 s25, s9, s23
	s_cselect_b32 s24, s48, s22
	v_add_u32_e32 v140, s53, v143
	s_cselect_b32 s23, s7, s51
	s_cselect_b32 s22, s49, s50
	s_add_i32 s56, 0, 0x14000
	ds_read_b128 v[146:149], v140
	ds_read_b128 v[150:153], v140 offset:1024
	ds_read_b128 v[154:157], v140 offset:2048
	ds_read_b128 v[158:161], v140 offset:3072
	v_add_u32_e32 v140, s56, v143
	ds_read_b128 v[162:165], v140
	ds_read_b128 v[166:169], v140 offset:1024
	ds_read_b128 v[170:173], v140 offset:2048
	ds_read_b128 v[178:181], v140 offset:3072
	v_lshl_add_u64 v[140:141], s[18:19], 0, v[136:137]
	s_add_i32 m0, s39, 0xc000
	ds_read_b128 v[190:193], v145
	ds_read_b128 v[194:197], v145 offset:1024
	ds_read_b128 v[198:201], v145 offset:2048
	ds_read_b128 v[202:205], v145 offset:3072
	ds_read_b128 v[206:209], v145 offset:4096
	ds_read_b128 v[228:231], v145 offset:5120
	ds_read_b128 v[232:235], v145 offset:6144
	ds_read_b128 v[236:239], v145 offset:7168
	global_load_lds_dwordx4 v[140:141], off
	v_lshl_add_u64 v[140:141], s[18:19], 0, v[138:139]
	s_add_i32 m0, s39, 0xe000
	s_nop 0
	global_load_lds_dwordx4 v[140:141], off
	s_waitcnt vmcnt(8)
	s_waitcnt lgkmcnt(0)
	s_barrier
	s_setprio 1
	s_waitcnt lgkmcnt(0)
	v_mfma_f32_16x16x32_bf16 v[126:129], v[146:149], v[190:193], v[126:129]
	v_mfma_f32_16x16x32_bf16 v[126:129], v[150:153], v[194:197], v[126:129]
	v_mfma_f32_16x16x32_bf16 v[122:125], v[154:157], v[190:193], v[122:125]
	v_mfma_f32_16x16x32_bf16 v[122:125], v[158:161], v[194:197], v[122:125]
	v_mfma_f32_16x16x32_bf16 v[118:121], v[146:149], v[198:201], v[118:121]
	v_mfma_f32_16x16x32_bf16 v[118:121], v[150:153], v[202:205], v[118:121]
	v_mfma_f32_16x16x32_bf16 v[110:113], v[154:157], v[198:201], v[110:113]
	v_mfma_f32_16x16x32_bf16 v[110:113], v[158:161], v[202:205], v[110:113]
	v_mfma_f32_16x16x32_bf16 v[102:105], v[146:149], v[206:209], v[102:105]
	v_mfma_f32_16x16x32_bf16 v[102:105], v[150:153], v[228:231], v[102:105]
	v_mfma_f32_16x16x32_bf16 v[94:97], v[154:157], v[206:209], v[94:97]
	v_mfma_f32_16x16x32_bf16 v[94:97], v[158:161], v[228:231], v[94:97]
	v_mfma_f32_16x16x32_bf16 v[86:89], v[146:149], v[232:235], v[86:89]
	v_mfma_f32_16x16x32_bf16 v[86:89], v[150:153], v[236:239], v[86:89]
	v_mfma_f32_16x16x32_bf16 v[78:81], v[154:157], v[232:235], v[78:81]
	v_mfma_f32_16x16x32_bf16 v[78:81], v[158:161], v[236:239], v[78:81]
	s_setprio 0
	s_setprio 1
	v_mfma_f32_16x16x32_bf16 v[114:117], v[162:165], v[190:193], v[114:117]
	v_mfma_f32_16x16x32_bf16 v[114:117], v[166:169], v[194:197], v[114:117]
	v_mfma_f32_16x16x32_bf16 v[106:109], v[170:173], v[190:193], v[106:109]
	v_mfma_f32_16x16x32_bf16 v[106:109], v[178:181], v[194:197], v[106:109]
	v_mfma_f32_16x16x32_bf16 v[98:101], v[162:165], v[198:201], v[98:101]
	v_mfma_f32_16x16x32_bf16 v[98:101], v[166:169], v[202:205], v[98:101]
	v_mfma_f32_16x16x32_bf16 v[90:93], v[170:173], v[198:201], v[90:93]
	v_mfma_f32_16x16x32_bf16 v[90:93], v[178:181], v[202:205], v[90:93]
	v_mfma_f32_16x16x32_bf16 v[82:85], v[162:165], v[206:209], v[82:85]
	v_mfma_f32_16x16x32_bf16 v[82:85], v[166:169], v[228:231], v[82:85]
	v_mfma_f32_16x16x32_bf16 v[74:77], v[170:173], v[206:209], v[74:77]
	v_mfma_f32_16x16x32_bf16 v[74:77], v[178:181], v[228:231], v[74:77]
	v_mfma_f32_16x16x32_bf16 v[70:73], v[162:165], v[232:235], v[70:73]
	v_mfma_f32_16x16x32_bf16 v[70:73], v[166:169], v[236:239], v[70:73]
	v_mfma_f32_16x16x32_bf16 v[66:69], v[170:173], v[232:235], v[66:69]
	v_mfma_f32_16x16x32_bf16 v[66:69], v[178:181], v[236:239], v[66:69]
	s_setprio 0
	s_barrier
	s_add_i32 s53, s53, s38
	v_lshl_add_u64 v[140:141], s[22:23], 0, v[0:1]
	s_mov_b32 m0, s53
	ds_read_b128 v[190:193], v145 offset:16384
	ds_read_b128 v[194:197], v145 offset:17408
	ds_read_b128 v[198:201], v145 offset:18432
	ds_read_b128 v[202:205], v145 offset:19456
	ds_read_b128 v[206:209], v145 offset:20480
	ds_read_b128 v[228:231], v145 offset:21504
	ds_read_b128 v[232:235], v145 offset:22528
	ds_read_b128 v[236:239], v145 offset:23552
	global_load_lds_dwordx4 v[140:141], off
	s_add_i32 m0, s53, 0x2000
	s_add_u32 s54, s22, 0x100000
	v_lshl_add_u64 v[186:187], s[22:23], 0, v[130:131]
	s_addc_u32 s55, s23, 0
	s_add_i32 s53, s56, s38
	global_load_lds_dwordx4 v[186:187], off
	v_lshl_add_u64 v[188:189], s[54:55], 0, v[0:1]
	s_mov_b32 m0, s53
	v_lshl_add_u64 v[210:211], s[24:25], 0, v[132:133]
	global_load_lds_dwordx4 v[188:189], off
	v_lshl_add_u64 v[188:189], s[54:55], 0, v[130:131]
	s_add_i32 m0, s53, 0x2000
	s_nop 0
	global_load_lds_dwordx4 v[188:189], off
	v_lshl_add_u64 v[188:189], s[24:25], 0, v[134:135]
	s_mov_b32 m0, s39
	s_nop 0
	global_load_lds_dwordx4 v[188:189], off
	s_mov_b32 m0, s40
	s_nop 0
	global_load_lds_dwordx4 v[210:211], off
	s_waitcnt vmcnt(8)
	s_waitcnt lgkmcnt(0)
	s_barrier
	s_setprio 1
	s_waitcnt lgkmcnt(0)
	v_mfma_f32_16x16x32_bf16 v[62:65], v[146:149], v[190:193], v[62:65]
	v_mfma_f32_16x16x32_bf16 v[62:65], v[150:153], v[194:197], v[62:65]
	v_mfma_f32_16x16x32_bf16 v[58:61], v[154:157], v[190:193], v[58:61]
	v_mfma_f32_16x16x32_bf16 v[58:61], v[158:161], v[194:197], v[58:61]
	v_mfma_f32_16x16x32_bf16 v[54:57], v[146:149], v[198:201], v[54:57]
	v_mfma_f32_16x16x32_bf16 v[54:57], v[150:153], v[202:205], v[54:57]
	v_mfma_f32_16x16x32_bf16 v[46:49], v[154:157], v[198:201], v[46:49]
	v_mfma_f32_16x16x32_bf16 v[46:49], v[158:161], v[202:205], v[46:49]
	v_mfma_f32_16x16x32_bf16 v[38:41], v[146:149], v[206:209], v[38:41]
	v_mfma_f32_16x16x32_bf16 v[38:41], v[150:153], v[228:231], v[38:41]
	v_mfma_f32_16x16x32_bf16 v[30:33], v[154:157], v[206:209], v[30:33]
	v_mfma_f32_16x16x32_bf16 v[30:33], v[158:161], v[228:231], v[30:33]
	v_mfma_f32_16x16x32_bf16 v[22:25], v[146:149], v[232:235], v[22:25]
	v_mfma_f32_16x16x32_bf16 v[22:25], v[150:153], v[236:239], v[22:25]
	v_mfma_f32_16x16x32_bf16 v[14:17], v[154:157], v[232:235], v[14:17]
	v_mfma_f32_16x16x32_bf16 v[14:17], v[158:161], v[236:239], v[14:17]
	s_setprio 0
	s_setprio 1
	v_mfma_f32_16x16x32_bf16 v[50:53], v[162:165], v[190:193], v[50:53]
	v_mfma_f32_16x16x32_bf16 v[50:53], v[166:169], v[194:197], v[50:53]
	v_mfma_f32_16x16x32_bf16 v[42:45], v[170:173], v[190:193], v[42:45]
	v_mfma_f32_16x16x32_bf16 v[42:45], v[178:181], v[194:197], v[42:45]
	v_mfma_f32_16x16x32_bf16 v[34:37], v[162:165], v[198:201], v[34:37]
	v_mfma_f32_16x16x32_bf16 v[34:37], v[166:169], v[202:205], v[34:37]
	v_mfma_f32_16x16x32_bf16 v[26:29], v[170:173], v[198:201], v[26:29]
	v_mfma_f32_16x16x32_bf16 v[26:29], v[178:181], v[202:205], v[26:29]
	v_mfma_f32_16x16x32_bf16 v[18:21], v[162:165], v[206:209], v[18:21]
	v_mfma_f32_16x16x32_bf16 v[18:21], v[166:169], v[228:231], v[18:21]
	v_mfma_f32_16x16x32_bf16 v[10:13], v[170:173], v[206:209], v[10:13]
	v_mfma_f32_16x16x32_bf16 v[10:13], v[178:181], v[228:231], v[10:13]
	v_mfma_f32_16x16x32_bf16 v[6:9], v[162:165], v[232:235], v[6:9]
	v_mfma_f32_16x16x32_bf16 v[6:9], v[166:169], v[236:239], v[6:9]
	v_mfma_f32_16x16x32_bf16 v[2:5], v[170:173], v[232:235], v[2:5]
	v_mfma_f32_16x16x32_bf16 v[2:5], v[178:181], v[236:239], v[2:5]
	s_setprio 0
	s_barrier
	s_add_i32 s53, 0, 0x18000
	s_add_i32 s54, 0, 0x1c000
	v_add_u32_e32 v158, s53, v143
	v_add_u32_e32 v175, s54, v143
	ds_read_b128 v[146:149], v158
	ds_read_b128 v[150:153], v158 offset:1024
	ds_read_b128 v[154:157], v158 offset:2048
	ds_read_b128 v[158:161], v158 offset:3072
	ds_read_b128 v[162:165], v175
	ds_read_b128 v[166:169], v175 offset:1024
	ds_read_b128 v[170:173], v175 offset:2048
	ds_read_b128 v[178:181], v175 offset:3072
	s_add_u32 s24, s24, 0x100000
	s_addc_u32 s25, s25, 0
	s_mov_b32 m0, s41
	v_lshl_add_u64 v[226:227], s[24:25], 0, v[134:135]
	ds_read_b128 v[190:193], v145 offset:32768
	ds_read_b128 v[194:197], v145 offset:33792
	ds_read_b128 v[198:201], v145 offset:34816
	ds_read_b128 v[202:205], v145 offset:35840
	ds_read_b128 v[206:209], v145 offset:36864
	ds_read_b128 v[228:231], v145 offset:37888
	ds_read_b128 v[232:235], v145 offset:38912
	ds_read_b128 v[236:239], v145 offset:39936
	global_load_lds_dwordx4 v[226:227], off
	v_lshl_add_u64 v[226:227], s[24:25], 0, v[132:133]
	s_mov_b32 m0, s42
	s_nop 0
	global_load_lds_dwordx4 v[226:227], off
	s_waitcnt vmcnt(8)
	s_waitcnt lgkmcnt(0)
	s_barrier
	s_setprio 1
	s_waitcnt lgkmcnt(0)
	v_mfma_f32_16x16x32_bf16 v[126:129], v[146:149], v[190:193], v[126:129]
	v_mfma_f32_16x16x32_bf16 v[126:129], v[150:153], v[194:197], v[126:129]
	v_mfma_f32_16x16x32_bf16 v[122:125], v[154:157], v[190:193], v[122:125]
	v_mfma_f32_16x16x32_bf16 v[122:125], v[158:161], v[194:197], v[122:125]
	v_mfma_f32_16x16x32_bf16 v[118:121], v[146:149], v[198:201], v[118:121]
	v_mfma_f32_16x16x32_bf16 v[118:121], v[150:153], v[202:205], v[118:121]
	v_mfma_f32_16x16x32_bf16 v[110:113], v[154:157], v[198:201], v[110:113]
	v_mfma_f32_16x16x32_bf16 v[110:113], v[158:161], v[202:205], v[110:113]
	v_mfma_f32_16x16x32_bf16 v[102:105], v[146:149], v[206:209], v[102:105]
	v_mfma_f32_16x16x32_bf16 v[102:105], v[150:153], v[228:231], v[102:105]
	v_mfma_f32_16x16x32_bf16 v[94:97], v[154:157], v[206:209], v[94:97]
	v_mfma_f32_16x16x32_bf16 v[94:97], v[158:161], v[228:231], v[94:97]
	v_mfma_f32_16x16x32_bf16 v[86:89], v[146:149], v[232:235], v[86:89]
	v_mfma_f32_16x16x32_bf16 v[86:89], v[150:153], v[236:239], v[86:89]
	v_mfma_f32_16x16x32_bf16 v[78:81], v[154:157], v[232:235], v[78:81]
	v_mfma_f32_16x16x32_bf16 v[78:81], v[158:161], v[236:239], v[78:81]
	s_setprio 0
	s_setprio 1
	v_mfma_f32_16x16x32_bf16 v[114:117], v[162:165], v[190:193], v[114:117]
	v_mfma_f32_16x16x32_bf16 v[114:117], v[166:169], v[194:197], v[114:117]
	v_mfma_f32_16x16x32_bf16 v[106:109], v[170:173], v[190:193], v[106:109]
	v_mfma_f32_16x16x32_bf16 v[106:109], v[178:181], v[194:197], v[106:109]
	v_mfma_f32_16x16x32_bf16 v[98:101], v[162:165], v[198:201], v[98:101]
	v_mfma_f32_16x16x32_bf16 v[98:101], v[166:169], v[202:205], v[98:101]
	v_mfma_f32_16x16x32_bf16 v[90:93], v[170:173], v[198:201], v[90:93]
	v_mfma_f32_16x16x32_bf16 v[90:93], v[178:181], v[202:205], v[90:93]
	v_mfma_f32_16x16x32_bf16 v[82:85], v[162:165], v[206:209], v[82:85]
	v_mfma_f32_16x16x32_bf16 v[82:85], v[166:169], v[228:231], v[82:85]
	v_mfma_f32_16x16x32_bf16 v[74:77], v[170:173], v[206:209], v[74:77]
	v_mfma_f32_16x16x32_bf16 v[74:77], v[178:181], v[228:231], v[74:77]
	v_mfma_f32_16x16x32_bf16 v[70:73], v[162:165], v[232:235], v[70:73]
	v_mfma_f32_16x16x32_bf16 v[70:73], v[166:169], v[236:239], v[70:73]
	v_mfma_f32_16x16x32_bf16 v[66:69], v[170:173], v[232:235], v[66:69]
	v_mfma_f32_16x16x32_bf16 v[66:69], v[178:181], v[236:239], v[66:69]
	s_setprio 0
	s_barrier
	s_add_i32 s24, s53, s38
	v_lshl_add_u64 v[140:141], v[140:141], 0, s[34:35]
	s_mov_b32 m0, s24
	ds_read_b128 v[190:193], v145 offset:49152
	ds_read_b128 v[194:197], v145 offset:50176
	ds_read_b128 v[198:201], v145 offset:51200
	ds_read_b128 v[202:205], v145 offset:52224
	ds_read_b128 v[206:209], v145 offset:53248
	ds_read_b128 v[228:231], v145 offset:54272
	ds_read_b128 v[232:235], v145 offset:55296
	ds_read_b128 v[236:239], v145 offset:56320
	global_load_lds_dwordx4 v[140:141], off
	s_add_i32 m0, s24, 0x2000
	s_add_u32 s22, s22, 0x100080
	v_lshl_add_u64 v[140:141], v[186:187], 0, s[34:35]
	s_addc_u32 s23, s23, 0
	s_add_i32 s24, s54, s38
	global_load_lds_dwordx4 v[140:141], off
	v_lshl_add_u64 v[140:141], s[22:23], 0, v[0:1]
	s_mov_b32 m0, s24
	s_nop 0
	global_load_lds_dwordx4 v[140:141], off
	v_lshl_add_u64 v[140:141], s[22:23], 0, v[130:131]
	s_add_i32 m0, s24, 0x2000
	s_nop 0
	global_load_lds_dwordx4 v[140:141], off
	v_lshl_add_u64 v[140:141], v[188:189], 0, s[34:35]
	s_mov_b32 m0, s43
	s_nop 0
	global_load_lds_dwordx4 v[140:141], off
	v_lshl_add_u64 v[140:141], v[210:211], 0, s[34:35]
	s_mov_b32 m0, s44
	s_nop 0
	global_load_lds_dwordx4 v[140:141], off
	s_waitcnt vmcnt(8)
	s_waitcnt lgkmcnt(0)
	s_barrier
	s_setprio 1
	s_waitcnt lgkmcnt(0)
	v_mfma_f32_16x16x32_bf16 v[62:65], v[146:149], v[190:193], v[62:65]
	v_mfma_f32_16x16x32_bf16 v[62:65], v[150:153], v[194:197], v[62:65]
	v_mfma_f32_16x16x32_bf16 v[58:61], v[154:157], v[190:193], v[58:61]
	v_mfma_f32_16x16x32_bf16 v[58:61], v[158:161], v[194:197], v[58:61]
	v_mfma_f32_16x16x32_bf16 v[54:57], v[146:149], v[198:201], v[54:57]
	v_mfma_f32_16x16x32_bf16 v[54:57], v[150:153], v[202:205], v[54:57]
	v_mfma_f32_16x16x32_bf16 v[46:49], v[154:157], v[198:201], v[46:49]
	v_mfma_f32_16x16x32_bf16 v[46:49], v[158:161], v[202:205], v[46:49]
	v_mfma_f32_16x16x32_bf16 v[38:41], v[146:149], v[206:209], v[38:41]
	v_mfma_f32_16x16x32_bf16 v[38:41], v[150:153], v[228:231], v[38:41]
	v_mfma_f32_16x16x32_bf16 v[30:33], v[154:157], v[206:209], v[30:33]
	v_mfma_f32_16x16x32_bf16 v[30:33], v[158:161], v[228:231], v[30:33]
	v_mfma_f32_16x16x32_bf16 v[22:25], v[146:149], v[232:235], v[22:25]
	v_mfma_f32_16x16x32_bf16 v[22:25], v[150:153], v[236:239], v[22:25]
	v_mfma_f32_16x16x32_bf16 v[14:17], v[154:157], v[232:235], v[14:17]
	v_mfma_f32_16x16x32_bf16 v[14:17], v[158:161], v[236:239], v[14:17]
	s_setprio 0
	s_setprio 1
	v_mfma_f32_16x16x32_bf16 v[50:53], v[162:165], v[190:193], v[50:53]
	v_mfma_f32_16x16x32_bf16 v[50:53], v[166:169], v[194:197], v[50:53]
	v_mfma_f32_16x16x32_bf16 v[42:45], v[170:173], v[190:193], v[42:45]
	v_mfma_f32_16x16x32_bf16 v[42:45], v[178:181], v[194:197], v[42:45]
	v_mfma_f32_16x16x32_bf16 v[34:37], v[162:165], v[198:201], v[34:37]
	v_mfma_f32_16x16x32_bf16 v[34:37], v[166:169], v[202:205], v[34:37]
	v_mfma_f32_16x16x32_bf16 v[26:29], v[170:173], v[198:201], v[26:29]
	v_mfma_f32_16x16x32_bf16 v[26:29], v[178:181], v[202:205], v[26:29]
	v_mfma_f32_16x16x32_bf16 v[18:21], v[162:165], v[206:209], v[18:21]
	v_mfma_f32_16x16x32_bf16 v[18:21], v[166:169], v[228:231], v[18:21]
	v_mfma_f32_16x16x32_bf16 v[10:13], v[170:173], v[206:209], v[10:13]
	v_mfma_f32_16x16x32_bf16 v[10:13], v[178:181], v[228:231], v[10:13]
	v_mfma_f32_16x16x32_bf16 v[6:9], v[162:165], v[232:235], v[6:9]
	v_mfma_f32_16x16x32_bf16 v[6:9], v[166:169], v[236:239], v[6:9]
	v_mfma_f32_16x16x32_bf16 v[2:5], v[170:173], v[232:235], v[2:5]
	v_mfma_f32_16x16x32_bf16 v[2:5], v[178:181], v[236:239], v[2:5]
	s_setprio 0
	s_barrier
	s_add_i32 s52, s52, 2
	s_add_u32 s18, s18, 0x100
	s_addc_u32 s19, s19, 0
	s_add_u32 s50, s50, 0x100
	s_addc_u32 s51, s51, 0
	s_cmp_gt_u32 s52, 61
	s_cbranch_scc0 .LBB0_575
	s_and_b64 vcc, exec, s[4:5]
	s_cbranch_vccz .LBB0_578
	s_barrier

.LBB0_721:
	s_add_u32 s18, s16, 0xfff00080
	s_addc_u32 s19, s17, -1
	s_add_i32 s53, 0, 0x10000
	s_cmp_eq_u32 s52, 60
	s_cselect_b32 s23, s7, s19
	s_cselect_b32 s22, s48, s18
	v_add_u32_e32 v140, s53, v143
	s_cselect_b32 s19, s5, s51
	s_cselect_b32 s18, s49, s50
	s_add_i32 s56, 0, 0x14000
	ds_read_b128 v[146:149], v140
	ds_read_b128 v[150:153], v140 offset:1024
	ds_read_b128 v[154:157], v140 offset:2048
	ds_read_b128 v[158:161], v140 offset:3072
	v_add_u32_e32 v140, s56, v143
	ds_read_b128 v[162:165], v140
	ds_read_b128 v[166:169], v140 offset:1024
	ds_read_b128 v[170:173], v140 offset:2048
	ds_read_b128 v[178:181], v140 offset:3072
	v_lshl_add_u64 v[140:141], s[16:17], 0, v[136:137]
	s_add_i32 m0, s31, 0xc000
	ds_read_b128 v[190:193], v145
	ds_read_b128 v[194:197], v145 offset:1024
	ds_read_b128 v[198:201], v145 offset:2048
	ds_read_b128 v[202:205], v145 offset:3072
	ds_read_b128 v[206:209], v145 offset:4096
	ds_read_b128 v[228:231], v145 offset:5120
	ds_read_b128 v[232:235], v145 offset:6144
	ds_read_b128 v[236:239], v145 offset:7168
	global_load_lds_dwordx4 v[140:141], off
	v_lshl_add_u64 v[140:141], s[16:17], 0, v[138:139]
	s_add_i32 m0, s31, 0xe000
	s_nop 0
	global_load_lds_dwordx4 v[140:141], off
	s_waitcnt vmcnt(8)
	s_waitcnt lgkmcnt(0)
	s_barrier
	s_setprio 1
	s_waitcnt lgkmcnt(0)
	v_mfma_f32_16x16x32_bf16 v[126:129], v[146:149], v[190:193], v[126:129]
	v_mfma_f32_16x16x32_bf16 v[126:129], v[150:153], v[194:197], v[126:129]
	v_mfma_f32_16x16x32_bf16 v[118:121], v[154:157], v[190:193], v[118:121]
	v_mfma_f32_16x16x32_bf16 v[118:121], v[158:161], v[194:197], v[118:121]
	v_mfma_f32_16x16x32_bf16 v[110:113], v[146:149], v[198:201], v[110:113]
	v_mfma_f32_16x16x32_bf16 v[110:113], v[150:153], v[202:205], v[110:113]
	v_mfma_f32_16x16x32_bf16 v[102:105], v[154:157], v[198:201], v[102:105]
	v_mfma_f32_16x16x32_bf16 v[102:105], v[158:161], v[202:205], v[102:105]
	v_mfma_f32_16x16x32_bf16 v[94:97], v[146:149], v[206:209], v[94:97]
	v_mfma_f32_16x16x32_bf16 v[94:97], v[150:153], v[228:231], v[94:97]
	v_mfma_f32_16x16x32_bf16 v[86:89], v[154:157], v[206:209], v[86:89]
	v_mfma_f32_16x16x32_bf16 v[86:89], v[158:161], v[228:231], v[86:89]
	v_mfma_f32_16x16x32_bf16 v[78:81], v[146:149], v[232:235], v[78:81]
	v_mfma_f32_16x16x32_bf16 v[78:81], v[150:153], v[236:239], v[78:81]
	v_mfma_f32_16x16x32_bf16 v[70:73], v[154:157], v[232:235], v[70:73]
	v_mfma_f32_16x16x32_bf16 v[70:73], v[158:161], v[236:239], v[70:73]
	s_setprio 0
	s_setprio 1
	v_mfma_f32_16x16x32_bf16 v[122:125], v[162:165], v[190:193], v[122:125]
	v_mfma_f32_16x16x32_bf16 v[122:125], v[166:169], v[194:197], v[122:125]
	v_mfma_f32_16x16x32_bf16 v[114:117], v[170:173], v[190:193], v[114:117]
	v_mfma_f32_16x16x32_bf16 v[114:117], v[178:181], v[194:197], v[114:117]
	v_mfma_f32_16x16x32_bf16 v[106:109], v[162:165], v[198:201], v[106:109]
	v_mfma_f32_16x16x32_bf16 v[106:109], v[166:169], v[202:205], v[106:109]
	v_mfma_f32_16x16x32_bf16 v[98:101], v[170:173], v[198:201], v[98:101]
	v_mfma_f32_16x16x32_bf16 v[98:101], v[178:181], v[202:205], v[98:101]
	v_mfma_f32_16x16x32_bf16 v[90:93], v[162:165], v[206:209], v[90:93]
	v_mfma_f32_16x16x32_bf16 v[90:93], v[166:169], v[228:231], v[90:93]
	v_mfma_f32_16x16x32_bf16 v[82:85], v[170:173], v[206:209], v[82:85]
	v_mfma_f32_16x16x32_bf16 v[82:85], v[178:181], v[228:231], v[82:85]
	v_mfma_f32_16x16x32_bf16 v[74:77], v[162:165], v[232:235], v[74:77]
	v_mfma_f32_16x16x32_bf16 v[74:77], v[166:169], v[236:239], v[74:77]
	v_mfma_f32_16x16x32_bf16 v[66:69], v[170:173], v[232:235], v[66:69]
	v_mfma_f32_16x16x32_bf16 v[66:69], v[178:181], v[236:239], v[66:69]
	s_setprio 0
	s_barrier
	s_add_i32 s53, s53, s26
	v_lshl_add_u64 v[140:141], s[18:19], 0, v[0:1]
	s_mov_b32 m0, s53
	ds_read_b128 v[190:193], v145 offset:16384
	ds_read_b128 v[194:197], v145 offset:17408
	ds_read_b128 v[198:201], v145 offset:18432
	ds_read_b128 v[202:205], v145 offset:19456
	ds_read_b128 v[206:209], v145 offset:20480
	ds_read_b128 v[228:231], v145 offset:21504
	ds_read_b128 v[232:235], v145 offset:22528
	ds_read_b128 v[236:239], v145 offset:23552
	global_load_lds_dwordx4 v[140:141], off
	s_add_i32 m0, s53, 0x2000
	s_add_u32 s54, s18, 0x100000
	v_lshl_add_u64 v[186:187], s[18:19], 0, v[130:131]
	s_addc_u32 s55, s19, 0
	s_add_i32 s53, s56, s26
	global_load_lds_dwordx4 v[186:187], off
	v_lshl_add_u64 v[188:189], s[54:55], 0, v[0:1]
	s_mov_b32 m0, s53
	v_lshl_add_u64 v[210:211], s[22:23], 0, v[132:133]
	global_load_lds_dwordx4 v[188:189], off
	v_lshl_add_u64 v[188:189], s[54:55], 0, v[130:131]
	s_add_i32 m0, s53, 0x2000
	s_nop 0
	global_load_lds_dwordx4 v[188:189], off
	v_lshl_add_u64 v[188:189], s[22:23], 0, v[134:135]
	s_mov_b32 m0, s31
	s_nop 0
	global_load_lds_dwordx4 v[188:189], off
	s_mov_b32 m0, s40
	s_nop 0
	global_load_lds_dwordx4 v[210:211], off
	s_waitcnt vmcnt(8)
	s_waitcnt lgkmcnt(0)
	s_barrier
	s_setprio 1
	s_waitcnt lgkmcnt(0)
	v_mfma_f32_16x16x32_bf16 v[62:65], v[146:149], v[190:193], v[62:65]
	v_mfma_f32_16x16x32_bf16 v[62:65], v[150:153], v[194:197], v[62:65]
	v_mfma_f32_16x16x32_bf16 v[54:57], v[154:157], v[190:193], v[54:57]
	v_mfma_f32_16x16x32_bf16 v[54:57], v[158:161], v[194:197], v[54:57]
	v_mfma_f32_16x16x32_bf16 v[46:49], v[146:149], v[198:201], v[46:49]
	v_mfma_f32_16x16x32_bf16 v[46:49], v[150:153], v[202:205], v[46:49]
	v_mfma_f32_16x16x32_bf16 v[38:41], v[154:157], v[198:201], v[38:41]
	v_mfma_f32_16x16x32_bf16 v[38:41], v[158:161], v[202:205], v[38:41]
	v_mfma_f32_16x16x32_bf16 v[30:33], v[146:149], v[206:209], v[30:33]
	v_mfma_f32_16x16x32_bf16 v[30:33], v[150:153], v[228:231], v[30:33]
	v_mfma_f32_16x16x32_bf16 v[22:25], v[154:157], v[206:209], v[22:25]
	v_mfma_f32_16x16x32_bf16 v[22:25], v[158:161], v[228:231], v[22:25]
	v_mfma_f32_16x16x32_bf16 v[14:17], v[146:149], v[232:235], v[14:17]
	v_mfma_f32_16x16x32_bf16 v[14:17], v[150:153], v[236:239], v[14:17]
	v_mfma_f32_16x16x32_bf16 v[6:9], v[154:157], v[232:235], v[6:9]
	v_mfma_f32_16x16x32_bf16 v[6:9], v[158:161], v[236:239], v[6:9]
	s_setprio 0
	s_setprio 1
	v_mfma_f32_16x16x32_bf16 v[58:61], v[162:165], v[190:193], v[58:61]
	v_mfma_f32_16x16x32_bf16 v[58:61], v[166:169], v[194:197], v[58:61]
	v_mfma_f32_16x16x32_bf16 v[50:53], v[170:173], v[190:193], v[50:53]
	v_mfma_f32_16x16x32_bf16 v[50:53], v[178:181], v[194:197], v[50:53]
	v_mfma_f32_16x16x32_bf16 v[42:45], v[162:165], v[198:201], v[42:45]
	v_mfma_f32_16x16x32_bf16 v[42:45], v[166:169], v[202:205], v[42:45]
	v_mfma_f32_16x16x32_bf16 v[34:37], v[170:173], v[198:201], v[34:37]
	v_mfma_f32_16x16x32_bf16 v[34:37], v[178:181], v[202:205], v[34:37]
	v_mfma_f32_16x16x32_bf16 v[26:29], v[162:165], v[206:209], v[26:29]
	v_mfma_f32_16x16x32_bf16 v[26:29], v[166:169], v[228:231], v[26:29]
	v_mfma_f32_16x16x32_bf16 v[18:21], v[170:173], v[206:209], v[18:21]
	v_mfma_f32_16x16x32_bf16 v[18:21], v[178:181], v[228:231], v[18:21]
	v_mfma_f32_16x16x32_bf16 v[10:13], v[162:165], v[232:235], v[10:13]
	v_mfma_f32_16x16x32_bf16 v[10:13], v[166:169], v[236:239], v[10:13]
	v_mfma_f32_16x16x32_bf16 v[2:5], v[170:173], v[232:235], v[2:5]
	v_mfma_f32_16x16x32_bf16 v[2:5], v[178:181], v[236:239], v[2:5]
	s_setprio 0
	s_barrier
	s_add_i32 s53, 0, 0x18000
	s_add_i32 s54, 0, 0x1c000
	v_add_u32_e32 v158, s53, v143
	v_add_u32_e32 v175, s54, v143
	ds_read_b128 v[146:149], v158
	ds_read_b128 v[150:153], v158 offset:1024
	ds_read_b128 v[154:157], v158 offset:2048
	ds_read_b128 v[158:161], v158 offset:3072
	ds_read_b128 v[162:165], v175
	ds_read_b128 v[166:169], v175 offset:1024
	ds_read_b128 v[170:173], v175 offset:2048
	ds_read_b128 v[178:181], v175 offset:3072
	s_add_u32 s22, s22, 0x100000
	s_addc_u32 s23, s23, 0
	s_mov_b32 m0, s41
	v_lshl_add_u64 v[226:227], s[22:23], 0, v[134:135]
	ds_read_b128 v[190:193], v145 offset:32768
	ds_read_b128 v[194:197], v145 offset:33792
	ds_read_b128 v[198:201], v145 offset:34816
	ds_read_b128 v[202:205], v145 offset:35840
	ds_read_b128 v[206:209], v145 offset:36864
	ds_read_b128 v[228:231], v145 offset:37888
	ds_read_b128 v[232:235], v145 offset:38912
	ds_read_b128 v[236:239], v145 offset:39936
	global_load_lds_dwordx4 v[226:227], off
	v_lshl_add_u64 v[226:227], s[22:23], 0, v[132:133]
	s_mov_b32 m0, s42
	s_nop 0
	global_load_lds_dwordx4 v[226:227], off
	s_waitcnt vmcnt(8)
	s_waitcnt lgkmcnt(0)
	s_barrier
	s_setprio 1
	s_waitcnt lgkmcnt(0)
	v_mfma_f32_16x16x32_bf16 v[126:129], v[146:149], v[190:193], v[126:129]
	v_mfma_f32_16x16x32_bf16 v[126:129], v[150:153], v[194:197], v[126:129]
	v_mfma_f32_16x16x32_bf16 v[118:121], v[154:157], v[190:193], v[118:121]
	v_mfma_f32_16x16x32_bf16 v[118:121], v[158:161], v[194:197], v[118:121]
	v_mfma_f32_16x16x32_bf16 v[110:113], v[146:149], v[198:201], v[110:113]
	v_mfma_f32_16x16x32_bf16 v[110:113], v[150:153], v[202:205], v[110:113]
	v_mfma_f32_16x16x32_bf16 v[102:105], v[154:157], v[198:201], v[102:105]
	v_mfma_f32_16x16x32_bf16 v[102:105], v[158:161], v[202:205], v[102:105]
	v_mfma_f32_16x16x32_bf16 v[94:97], v[146:149], v[206:209], v[94:97]
	v_mfma_f32_16x16x32_bf16 v[94:97], v[150:153], v[228:231], v[94:97]
	v_mfma_f32_16x16x32_bf16 v[86:89], v[154:157], v[206:209], v[86:89]
	v_mfma_f32_16x16x32_bf16 v[86:89], v[158:161], v[228:231], v[86:89]
	v_mfma_f32_16x16x32_bf16 v[78:81], v[146:149], v[232:235], v[78:81]
	v_mfma_f32_16x16x32_bf16 v[78:81], v[150:153], v[236:239], v[78:81]
	v_mfma_f32_16x16x32_bf16 v[70:73], v[154:157], v[232:235], v[70:73]
	v_mfma_f32_16x16x32_bf16 v[70:73], v[158:161], v[236:239], v[70:73]
	s_setprio 0
	s_setprio 1
	v_mfma_f32_16x16x32_bf16 v[122:125], v[162:165], v[190:193], v[122:125]
	v_mfma_f32_16x16x32_bf16 v[122:125], v[166:169], v[194:197], v[122:125]
	v_mfma_f32_16x16x32_bf16 v[114:117], v[170:173], v[190:193], v[114:117]
	v_mfma_f32_16x16x32_bf16 v[114:117], v[178:181], v[194:197], v[114:117]
	v_mfma_f32_16x16x32_bf16 v[106:109], v[162:165], v[198:201], v[106:109]
	v_mfma_f32_16x16x32_bf16 v[106:109], v[166:169], v[202:205], v[106:109]
	v_mfma_f32_16x16x32_bf16 v[98:101], v[170:173], v[198:201], v[98:101]
	v_mfma_f32_16x16x32_bf16 v[98:101], v[178:181], v[202:205], v[98:101]
	v_mfma_f32_16x16x32_bf16 v[90:93], v[162:165], v[206:209], v[90:93]
	v_mfma_f32_16x16x32_bf16 v[90:93], v[166:169], v[228:231], v[90:93]
	v_mfma_f32_16x16x32_bf16 v[82:85], v[170:173], v[206:209], v[82:85]
	v_mfma_f32_16x16x32_bf16 v[82:85], v[178:181], v[228:231], v[82:85]
	v_mfma_f32_16x16x32_bf16 v[74:77], v[162:165], v[232:235], v[74:77]
	v_mfma_f32_16x16x32_bf16 v[74:77], v[166:169], v[236:239], v[74:77]
	v_mfma_f32_16x16x32_bf16 v[66:69], v[170:173], v[232:235], v[66:69]
	v_mfma_f32_16x16x32_bf16 v[66:69], v[178:181], v[236:239], v[66:69]
	s_setprio 0
	s_barrier
	s_add_i32 s22, s53, s26
	v_lshl_add_u64 v[140:141], v[140:141], 0, s[34:35]
	s_mov_b32 m0, s22
	ds_read_b128 v[190:193], v145 offset:49152
	ds_read_b128 v[194:197], v145 offset:50176
	ds_read_b128 v[198:201], v145 offset:51200
	ds_read_b128 v[202:205], v145 offset:52224
	ds_read_b128 v[206:209], v145 offset:53248
	ds_read_b128 v[228:231], v145 offset:54272
	ds_read_b128 v[232:235], v145 offset:55296
	ds_read_b128 v[236:239], v145 offset:56320
	global_load_lds_dwordx4 v[140:141], off
	s_add_i32 m0, s22, 0x2000
	s_add_u32 s18, s18, 0x100080
	v_lshl_add_u64 v[140:141], v[186:187], 0, s[34:35]
	s_addc_u32 s19, s19, 0
	s_add_i32 s22, s54, s26
	global_load_lds_dwordx4 v[140:141], off
	v_lshl_add_u64 v[140:141], s[18:19], 0, v[0:1]
	s_mov_b32 m0, s22
	s_nop 0
	global_load_lds_dwordx4 v[140:141], off
	v_lshl_add_u64 v[140:141], s[18:19], 0, v[130:131]
	s_add_i32 m0, s22, 0x2000
	s_nop 0
	global_load_lds_dwordx4 v[140:141], off
	v_lshl_add_u64 v[140:141], v[188:189], 0, s[34:35]
	s_mov_b32 m0, s43
	s_nop 0
	global_load_lds_dwordx4 v[140:141], off
	v_lshl_add_u64 v[140:141], v[210:211], 0, s[34:35]
	s_mov_b32 m0, s44
	s_nop 0
	global_load_lds_dwordx4 v[140:141], off
	s_waitcnt vmcnt(8)
	s_waitcnt lgkmcnt(0)
	s_barrier
	s_setprio 1
	s_waitcnt lgkmcnt(0)
	v_mfma_f32_16x16x32_bf16 v[62:65], v[146:149], v[190:193], v[62:65]
	v_mfma_f32_16x16x32_bf16 v[62:65], v[150:153], v[194:197], v[62:65]
	v_mfma_f32_16x16x32_bf16 v[54:57], v[154:157], v[190:193], v[54:57]
	v_mfma_f32_16x16x32_bf16 v[54:57], v[158:161], v[194:197], v[54:57]
	v_mfma_f32_16x16x32_bf16 v[46:49], v[146:149], v[198:201], v[46:49]
	v_mfma_f32_16x16x32_bf16 v[46:49], v[150:153], v[202:205], v[46:49]
	v_mfma_f32_16x16x32_bf16 v[38:41], v[154:157], v[198:201], v[38:41]
	v_mfma_f32_16x16x32_bf16 v[38:41], v[158:161], v[202:205], v[38:41]
	v_mfma_f32_16x16x32_bf16 v[30:33], v[146:149], v[206:209], v[30:33]
	v_mfma_f32_16x16x32_bf16 v[30:33], v[150:153], v[228:231], v[30:33]
	v_mfma_f32_16x16x32_bf16 v[22:25], v[154:157], v[206:209], v[22:25]
	v_mfma_f32_16x16x32_bf16 v[22:25], v[158:161], v[228:231], v[22:25]
	v_mfma_f32_16x16x32_bf16 v[14:17], v[146:149], v[232:235], v[14:17]
	v_mfma_f32_16x16x32_bf16 v[14:17], v[150:153], v[236:239], v[14:17]
	v_mfma_f32_16x16x32_bf16 v[6:9], v[154:157], v[232:235], v[6:9]
	v_mfma_f32_16x16x32_bf16 v[6:9], v[158:161], v[236:239], v[6:9]
	s_setprio 0
	s_setprio 1
	v_mfma_f32_16x16x32_bf16 v[58:61], v[162:165], v[190:193], v[58:61]
	v_mfma_f32_16x16x32_bf16 v[58:61], v[166:169], v[194:197], v[58:61]
	v_mfma_f32_16x16x32_bf16 v[50:53], v[170:173], v[190:193], v[50:53]
	v_mfma_f32_16x16x32_bf16 v[50:53], v[178:181], v[194:197], v[50:53]
	v_mfma_f32_16x16x32_bf16 v[42:45], v[162:165], v[198:201], v[42:45]
	v_mfma_f32_16x16x32_bf16 v[42:45], v[166:169], v[202:205], v[42:45]
	v_mfma_f32_16x16x32_bf16 v[34:37], v[170:173], v[198:201], v[34:37]
	v_mfma_f32_16x16x32_bf16 v[34:37], v[178:181], v[202:205], v[34:37]
	v_mfma_f32_16x16x32_bf16 v[26:29], v[162:165], v[206:209], v[26:29]
	v_mfma_f32_16x16x32_bf16 v[26:29], v[166:169], v[228:231], v[26:29]
	v_mfma_f32_16x16x32_bf16 v[18:21], v[170:173], v[206:209], v[18:21]
	v_mfma_f32_16x16x32_bf16 v[18:21], v[178:181], v[228:231], v[18:21]
	v_mfma_f32_16x16x32_bf16 v[10:13], v[162:165], v[232:235], v[10:13]
	v_mfma_f32_16x16x32_bf16 v[10:13], v[166:169], v[236:239], v[10:13]
	v_mfma_f32_16x16x32_bf16 v[2:5], v[170:173], v[232:235], v[2:5]
	v_mfma_f32_16x16x32_bf16 v[2:5], v[178:181], v[236:239], v[2:5]
	s_setprio 0
	s_barrier
	s_add_i32 s52, s52, 2
	s_add_u32 s16, s16, 0x100
	s_addc_u32 s17, s17, 0
	s_add_u32 s50, s50, 0x100
	s_addc_u32 s51, s51, 0
	s_cmp_gt_u32 s52, 61
	s_cbranch_scc0 .LBB0_721
	s_and_b64 vcc, exec, s[2:3]
	s_cbranch_vccz .LBB0_724
	s_barrier

.LBB0_805:
	s_add_u32 s16, s14, 0x100
	s_addc_u32 s17, s15, 0
	s_add_i32 s49, 0, 0x10000
	s_cmpk_eq_i32 s48, 0xa8
	s_cselect_b32 s23, s5, s17
	s_cselect_b32 s22, s4, s16
	v_add_u32_e32 v140, s49, v143
	s_cselect_b32 s19, s9, s47
	s_cselect_b32 s18, s8, s46
	s_add_i32 s50, 0, 0x14000
	ds_read_b128 v[146:149], v140
	ds_read_b128 v[150:153], v140 offset:1024
	ds_read_b128 v[154:157], v140 offset:2048
	ds_read_b128 v[158:161], v140 offset:3072
	v_add_u32_e32 v140, s50, v143
	ds_read_b128 v[162:165], v140
	ds_read_b128 v[166:169], v140 offset:1024
	ds_read_b128 v[170:173], v140 offset:2048
	ds_read_b128 v[178:181], v140 offset:3072
	v_lshl_add_u64 v[140:141], s[14:15], 0, v[136:137]
	s_add_i32 m0, s31, 0xc000
	ds_read_b128 v[190:193], v145
	ds_read_b128 v[194:197], v145 offset:1024
	ds_read_b128 v[198:201], v145 offset:2048
	ds_read_b128 v[202:205], v145 offset:3072
	ds_read_b128 v[206:209], v145 offset:4096
	ds_read_b128 v[228:231], v145 offset:5120
	ds_read_b128 v[232:235], v145 offset:6144
	ds_read_b128 v[236:239], v145 offset:7168
	global_load_lds_dwordx4 v[140:141], off
	v_lshl_add_u64 v[140:141], s[14:15], 0, v[138:139]
	s_add_i32 m0, s31, 0xe000
	s_nop 0
	global_load_lds_dwordx4 v[140:141], off
	s_waitcnt vmcnt(8)
	s_waitcnt lgkmcnt(0)
	s_barrier
	s_setprio 1
	s_waitcnt lgkmcnt(0)
	v_mfma_f32_16x16x32_bf16 v[126:129], v[146:149], v[190:193], v[126:129]
	v_mfma_f32_16x16x32_bf16 v[126:129], v[150:153], v[194:197], v[126:129]
	v_mfma_f32_16x16x32_bf16 v[122:125], v[154:157], v[190:193], v[122:125]
	v_mfma_f32_16x16x32_bf16 v[122:125], v[158:161], v[194:197], v[122:125]
	v_mfma_f32_16x16x32_bf16 v[118:121], v[146:149], v[198:201], v[118:121]
	v_mfma_f32_16x16x32_bf16 v[118:121], v[150:153], v[202:205], v[118:121]
	v_mfma_f32_16x16x32_bf16 v[110:113], v[154:157], v[198:201], v[110:113]
	v_mfma_f32_16x16x32_bf16 v[110:113], v[158:161], v[202:205], v[110:113]
	v_mfma_f32_16x16x32_bf16 v[102:105], v[146:149], v[206:209], v[102:105]
	v_mfma_f32_16x16x32_bf16 v[102:105], v[150:153], v[228:231], v[102:105]
	v_mfma_f32_16x16x32_bf16 v[94:97], v[154:157], v[206:209], v[94:97]
	v_mfma_f32_16x16x32_bf16 v[94:97], v[158:161], v[228:231], v[94:97]
	v_mfma_f32_16x16x32_bf16 v[86:89], v[146:149], v[232:235], v[86:89]
	v_mfma_f32_16x16x32_bf16 v[86:89], v[150:153], v[236:239], v[86:89]
	v_mfma_f32_16x16x32_bf16 v[78:81], v[154:157], v[232:235], v[78:81]
	v_mfma_f32_16x16x32_bf16 v[78:81], v[158:161], v[236:239], v[78:81]
	s_setprio 0
	s_setprio 1
	v_mfma_f32_16x16x32_bf16 v[114:117], v[162:165], v[190:193], v[114:117]
	v_mfma_f32_16x16x32_bf16 v[114:117], v[166:169], v[194:197], v[114:117]
	v_mfma_f32_16x16x32_bf16 v[106:109], v[170:173], v[190:193], v[106:109]
	v_mfma_f32_16x16x32_bf16 v[106:109], v[178:181], v[194:197], v[106:109]
	v_mfma_f32_16x16x32_bf16 v[98:101], v[162:165], v[198:201], v[98:101]
	v_mfma_f32_16x16x32_bf16 v[98:101], v[166:169], v[202:205], v[98:101]
	v_mfma_f32_16x16x32_bf16 v[90:93], v[170:173], v[198:201], v[90:93]
	v_mfma_f32_16x16x32_bf16 v[90:93], v[178:181], v[202:205], v[90:93]
	v_mfma_f32_16x16x32_bf16 v[82:85], v[162:165], v[206:209], v[82:85]
	v_mfma_f32_16x16x32_bf16 v[82:85], v[166:169], v[228:231], v[82:85]
	v_mfma_f32_16x16x32_bf16 v[74:77], v[170:173], v[206:209], v[74:77]
	v_mfma_f32_16x16x32_bf16 v[74:77], v[178:181], v[228:231], v[74:77]
	v_mfma_f32_16x16x32_bf16 v[70:73], v[162:165], v[232:235], v[70:73]
	v_mfma_f32_16x16x32_bf16 v[70:73], v[166:169], v[236:239], v[70:73]
	v_mfma_f32_16x16x32_bf16 v[66:69], v[170:173], v[232:235], v[66:69]
	v_mfma_f32_16x16x32_bf16 v[66:69], v[178:181], v[236:239], v[66:69]
	s_setprio 0
	s_barrier
	s_add_i32 s14, s49, s26
	v_lshl_add_u64 v[140:141], s[18:19], 0, v[0:1]
	s_mov_b32 m0, s14
	ds_read_b128 v[190:193], v145 offset:16384
	ds_read_b128 v[194:197], v145 offset:17408
	ds_read_b128 v[198:201], v145 offset:18432
	ds_read_b128 v[202:205], v145 offset:19456
	ds_read_b128 v[206:209], v145 offset:20480
	ds_read_b128 v[228:231], v145 offset:21504
	ds_read_b128 v[232:235], v145 offset:22528
	ds_read_b128 v[236:239], v145 offset:23552
	global_load_lds_dwordx4 v[140:141], off
	s_add_i32 m0, s14, 0x2000
	s_add_u32 s14, s18, 0x2b0000
	v_lshl_add_u64 v[186:187], s[18:19], 0, v[130:131]
	s_addc_u32 s15, s19, 0
	s_add_i32 s49, s50, s26
	global_load_lds_dwordx4 v[186:187], off
	v_lshl_add_u64 v[188:189], s[14:15], 0, v[0:1]
	s_mov_b32 m0, s49
	v_lshl_add_u64 v[210:211], s[22:23], 0, v[132:133]
	global_load_lds_dwordx4 v[188:189], off
	v_lshl_add_u64 v[188:189], s[14:15], 0, v[130:131]
	s_add_i32 m0, s49, 0x2000
	s_nop 0
	global_load_lds_dwordx4 v[188:189], off
	v_lshl_add_u64 v[188:189], s[22:23], 0, v[134:135]
	s_mov_b32 m0, s31
	s_nop 0
	global_load_lds_dwordx4 v[188:189], off
	s_mov_b32 m0, s36
	s_nop 0
	global_load_lds_dwordx4 v[210:211], off
	s_waitcnt vmcnt(8)
	s_waitcnt lgkmcnt(0)
	s_barrier
	s_setprio 1
	s_waitcnt lgkmcnt(0)
	v_mfma_f32_16x16x32_bf16 v[62:65], v[146:149], v[190:193], v[62:65]
	v_mfma_f32_16x16x32_bf16 v[62:65], v[150:153], v[194:197], v[62:65]
	v_mfma_f32_16x16x32_bf16 v[58:61], v[154:157], v[190:193], v[58:61]
	v_mfma_f32_16x16x32_bf16 v[58:61], v[158:161], v[194:197], v[58:61]
	v_mfma_f32_16x16x32_bf16 v[54:57], v[146:149], v[198:201], v[54:57]
	v_mfma_f32_16x16x32_bf16 v[54:57], v[150:153], v[202:205], v[54:57]
	v_mfma_f32_16x16x32_bf16 v[46:49], v[154:157], v[198:201], v[46:49]
	v_mfma_f32_16x16x32_bf16 v[46:49], v[158:161], v[202:205], v[46:49]
	v_mfma_f32_16x16x32_bf16 v[38:41], v[146:149], v[206:209], v[38:41]
	v_mfma_f32_16x16x32_bf16 v[38:41], v[150:153], v[228:231], v[38:41]
	v_mfma_f32_16x16x32_bf16 v[30:33], v[154:157], v[206:209], v[30:33]
	v_mfma_f32_16x16x32_bf16 v[30:33], v[158:161], v[228:231], v[30:33]
	v_mfma_f32_16x16x32_bf16 v[22:25], v[146:149], v[232:235], v[22:25]
	v_mfma_f32_16x16x32_bf16 v[22:25], v[150:153], v[236:239], v[22:25]
	v_mfma_f32_16x16x32_bf16 v[14:17], v[154:157], v[232:235], v[14:17]
	v_mfma_f32_16x16x32_bf16 v[14:17], v[158:161], v[236:239], v[14:17]
	s_setprio 0
	s_setprio 1
	v_mfma_f32_16x16x32_bf16 v[50:53], v[162:165], v[190:193], v[50:53]
	v_mfma_f32_16x16x32_bf16 v[50:53], v[166:169], v[194:197], v[50:53]
	v_mfma_f32_16x16x32_bf16 v[42:45], v[170:173], v[190:193], v[42:45]
	v_mfma_f32_16x16x32_bf16 v[42:45], v[178:181], v[194:197], v[42:45]
	v_mfma_f32_16x16x32_bf16 v[34:37], v[162:165], v[198:201], v[34:37]
	v_mfma_f32_16x16x32_bf16 v[34:37], v[166:169], v[202:205], v[34:37]
	v_mfma_f32_16x16x32_bf16 v[26:29], v[170:173], v[198:201], v[26:29]
	v_mfma_f32_16x16x32_bf16 v[26:29], v[178:181], v[202:205], v[26:29]
	v_mfma_f32_16x16x32_bf16 v[18:21], v[162:165], v[206:209], v[18:21]
	v_mfma_f32_16x16x32_bf16 v[18:21], v[166:169], v[228:231], v[18:21]
	v_mfma_f32_16x16x32_bf16 v[10:13], v[170:173], v[206:209], v[10:13]
	v_mfma_f32_16x16x32_bf16 v[10:13], v[178:181], v[228:231], v[10:13]
	v_mfma_f32_16x16x32_bf16 v[6:9], v[162:165], v[232:235], v[6:9]
	v_mfma_f32_16x16x32_bf16 v[6:9], v[166:169], v[236:239], v[6:9]
	v_mfma_f32_16x16x32_bf16 v[2:5], v[170:173], v[232:235], v[2:5]
	v_mfma_f32_16x16x32_bf16 v[2:5], v[178:181], v[236:239], v[2:5]
	s_setprio 0
	s_barrier
	s_add_i32 s49, 0, 0x18000
	s_add_i32 s50, 0, 0x1c000
	v_add_u32_e32 v158, s49, v143
	v_add_u32_e32 v175, s50, v143
	ds_read_b128 v[146:149], v158
	ds_read_b128 v[150:153], v158 offset:1024
	ds_read_b128 v[154:157], v158 offset:2048
	ds_read_b128 v[158:161], v158 offset:3072
	ds_read_b128 v[162:165], v175
	ds_read_b128 v[166:169], v175 offset:1024
	ds_read_b128 v[170:173], v175 offset:2048
	ds_read_b128 v[178:181], v175 offset:3072
	s_add_u32 s14, s22, 0x2b0000
	s_addc_u32 s15, s23, 0
	s_mov_b32 m0, s37
	v_lshl_add_u64 v[226:227], s[14:15], 0, v[134:135]
	ds_read_b128 v[190:193], v145 offset:32768
	ds_read_b128 v[194:197], v145 offset:33792
	ds_read_b128 v[198:201], v145 offset:34816
	ds_read_b128 v[202:205], v145 offset:35840
	ds_read_b128 v[206:209], v145 offset:36864
	ds_read_b128 v[228:231], v145 offset:37888
	ds_read_b128 v[232:235], v145 offset:38912
	ds_read_b128 v[236:239], v145 offset:39936
	global_load_lds_dwordx4 v[226:227], off
	v_lshl_add_u64 v[226:227], s[14:15], 0, v[132:133]
	s_mov_b32 m0, s38
	s_nop 0
	global_load_lds_dwordx4 v[226:227], off
	s_waitcnt vmcnt(8)
	s_waitcnt lgkmcnt(0)
	s_barrier
	s_setprio 1
	s_waitcnt lgkmcnt(0)
	v_mfma_f32_16x16x32_bf16 v[126:129], v[146:149], v[190:193], v[126:129]
	v_mfma_f32_16x16x32_bf16 v[126:129], v[150:153], v[194:197], v[126:129]
	v_mfma_f32_16x16x32_bf16 v[122:125], v[154:157], v[190:193], v[122:125]
	v_mfma_f32_16x16x32_bf16 v[122:125], v[158:161], v[194:197], v[122:125]
	v_mfma_f32_16x16x32_bf16 v[118:121], v[146:149], v[198:201], v[118:121]
	v_mfma_f32_16x16x32_bf16 v[118:121], v[150:153], v[202:205], v[118:121]
	v_mfma_f32_16x16x32_bf16 v[110:113], v[154:157], v[198:201], v[110:113]
	v_mfma_f32_16x16x32_bf16 v[110:113], v[158:161], v[202:205], v[110:113]
	v_mfma_f32_16x16x32_bf16 v[102:105], v[146:149], v[206:209], v[102:105]
	v_mfma_f32_16x16x32_bf16 v[102:105], v[150:153], v[228:231], v[102:105]
	v_mfma_f32_16x16x32_bf16 v[94:97], v[154:157], v[206:209], v[94:97]
	v_mfma_f32_16x16x32_bf16 v[94:97], v[158:161], v[228:231], v[94:97]
	v_mfma_f32_16x16x32_bf16 v[86:89], v[146:149], v[232:235], v[86:89]
	v_mfma_f32_16x16x32_bf16 v[86:89], v[150:153], v[236:239], v[86:89]
	v_mfma_f32_16x16x32_bf16 v[78:81], v[154:157], v[232:235], v[78:81]
	v_mfma_f32_16x16x32_bf16 v[78:81], v[158:161], v[236:239], v[78:81]
	s_setprio 0
	s_setprio 1
	v_mfma_f32_16x16x32_bf16 v[114:117], v[162:165], v[190:193], v[114:117]
	v_mfma_f32_16x16x32_bf16 v[114:117], v[166:169], v[194:197], v[114:117]
	v_mfma_f32_16x16x32_bf16 v[106:109], v[170:173], v[190:193], v[106:109]
	v_mfma_f32_16x16x32_bf16 v[106:109], v[178:181], v[194:197], v[106:109]
	v_mfma_f32_16x16x32_bf16 v[98:101], v[162:165], v[198:201], v[98:101]
	v_mfma_f32_16x16x32_bf16 v[98:101], v[166:169], v[202:205], v[98:101]
	v_mfma_f32_16x16x32_bf16 v[90:93], v[170:173], v[198:201], v[90:93]
	v_mfma_f32_16x16x32_bf16 v[90:93], v[178:181], v[202:205], v[90:93]
	v_mfma_f32_16x16x32_bf16 v[82:85], v[162:165], v[206:209], v[82:85]
	v_mfma_f32_16x16x32_bf16 v[82:85], v[166:169], v[228:231], v[82:85]
	v_mfma_f32_16x16x32_bf16 v[74:77], v[170:173], v[206:209], v[74:77]
	v_mfma_f32_16x16x32_bf16 v[74:77], v[178:181], v[228:231], v[74:77]
	v_mfma_f32_16x16x32_bf16 v[70:73], v[162:165], v[232:235], v[70:73]
	v_mfma_f32_16x16x32_bf16 v[70:73], v[166:169], v[236:239], v[70:73]
	v_mfma_f32_16x16x32_bf16 v[66:69], v[170:173], v[232:235], v[66:69]
	v_mfma_f32_16x16x32_bf16 v[66:69], v[178:181], v[236:239], v[66:69]
	s_setprio 0
	s_barrier
	s_add_i32 s14, s49, s26
	v_lshl_add_u64 v[140:141], v[140:141], 0, s[34:35]
	s_mov_b32 m0, s14
	ds_read_b128 v[190:193], v145 offset:49152
	ds_read_b128 v[194:197], v145 offset:50176
	ds_read_b128 v[198:201], v145 offset:51200
	ds_read_b128 v[202:205], v145 offset:52224
	ds_read_b128 v[206:209], v145 offset:53248
	ds_read_b128 v[228:231], v145 offset:54272
	ds_read_b128 v[232:235], v145 offset:55296
	ds_read_b128 v[236:239], v145 offset:56320
	global_load_lds_dwordx4 v[140:141], off
	s_add_i32 m0, s14, 0x2000
	s_add_u32 s14, s18, 0x2b0080
	v_lshl_add_u64 v[140:141], v[186:187], 0, s[34:35]
	s_addc_u32 s15, s19, 0
	s_add_i32 s18, s50, s26
	global_load_lds_dwordx4 v[140:141], off
	v_lshl_add_u64 v[140:141], s[14:15], 0, v[0:1]
	s_mov_b32 m0, s18
	s_nop 0
	global_load_lds_dwordx4 v[140:141], off
	v_lshl_add_u64 v[140:141], s[14:15], 0, v[130:131]
	s_add_i32 m0, s18, 0x2000
	s_nop 0
	global_load_lds_dwordx4 v[140:141], off
	v_lshl_add_u64 v[140:141], v[188:189], 0, s[34:35]
	s_mov_b32 m0, s39
	s_nop 0
	global_load_lds_dwordx4 v[140:141], off
	v_lshl_add_u64 v[140:141], v[210:211], 0, s[34:35]
	s_mov_b32 m0, s40
	s_nop 0
	global_load_lds_dwordx4 v[140:141], off
	s_waitcnt vmcnt(8)
	s_waitcnt lgkmcnt(0)
	s_barrier
	s_setprio 1
	s_waitcnt lgkmcnt(0)
	v_mfma_f32_16x16x32_bf16 v[62:65], v[146:149], v[190:193], v[62:65]
	v_mfma_f32_16x16x32_bf16 v[62:65], v[150:153], v[194:197], v[62:65]
	v_mfma_f32_16x16x32_bf16 v[58:61], v[154:157], v[190:193], v[58:61]
	v_mfma_f32_16x16x32_bf16 v[58:61], v[158:161], v[194:197], v[58:61]
	v_mfma_f32_16x16x32_bf16 v[54:57], v[146:149], v[198:201], v[54:57]
	v_mfma_f32_16x16x32_bf16 v[54:57], v[150:153], v[202:205], v[54:57]
	v_mfma_f32_16x16x32_bf16 v[46:49], v[154:157], v[198:201], v[46:49]
	v_mfma_f32_16x16x32_bf16 v[46:49], v[158:161], v[202:205], v[46:49]
	v_mfma_f32_16x16x32_bf16 v[38:41], v[146:149], v[206:209], v[38:41]
	v_mfma_f32_16x16x32_bf16 v[38:41], v[150:153], v[228:231], v[38:41]
	v_mfma_f32_16x16x32_bf16 v[30:33], v[154:157], v[206:209], v[30:33]
	v_mfma_f32_16x16x32_bf16 v[30:33], v[158:161], v[228:231], v[30:33]
	v_mfma_f32_16x16x32_bf16 v[22:25], v[146:149], v[232:235], v[22:25]
	v_mfma_f32_16x16x32_bf16 v[22:25], v[150:153], v[236:239], v[22:25]
	v_mfma_f32_16x16x32_bf16 v[14:17], v[154:157], v[232:235], v[14:17]
	v_mfma_f32_16x16x32_bf16 v[14:17], v[158:161], v[236:239], v[14:17]
	s_setprio 0
	s_setprio 1
	v_mfma_f32_16x16x32_bf16 v[50:53], v[162:165], v[190:193], v[50:53]
	v_mfma_f32_16x16x32_bf16 v[50:53], v[166:169], v[194:197], v[50:53]
	v_mfma_f32_16x16x32_bf16 v[42:45], v[170:173], v[190:193], v[42:45]
	v_mfma_f32_16x16x32_bf16 v[42:45], v[178:181], v[194:197], v[42:45]
	v_mfma_f32_16x16x32_bf16 v[34:37], v[162:165], v[198:201], v[34:37]
	v_mfma_f32_16x16x32_bf16 v[34:37], v[166:169], v[202:205], v[34:37]
	v_mfma_f32_16x16x32_bf16 v[26:29], v[170:173], v[198:201], v[26:29]
	v_mfma_f32_16x16x32_bf16 v[26:29], v[178:181], v[202:205], v[26:29]
	v_mfma_f32_16x16x32_bf16 v[18:21], v[162:165], v[206:209], v[18:21]
	v_mfma_f32_16x16x32_bf16 v[18:21], v[166:169], v[228:231], v[18:21]
	v_mfma_f32_16x16x32_bf16 v[10:13], v[170:173], v[206:209], v[10:13]
	v_mfma_f32_16x16x32_bf16 v[10:13], v[178:181], v[228:231], v[10:13]
	v_mfma_f32_16x16x32_bf16 v[6:9], v[162:165], v[232:235], v[6:9]
	v_mfma_f32_16x16x32_bf16 v[6:9], v[166:169], v[236:239], v[6:9]
	v_mfma_f32_16x16x32_bf16 v[2:5], v[170:173], v[232:235], v[2:5]
	v_mfma_f32_16x16x32_bf16 v[2:5], v[178:181], v[236:239], v[2:5]
	s_setprio 0
	s_barrier
	s_add_i32 s48, s48, 2
	s_add_u32 s46, s46, 0x100
	s_addc_u32 s47, s47, 0
	s_cmpk_gt_u32 s48, 0xa9
	s_mov_b64 s[14:15], s[16:17]
	s_cbranch_scc0 .LBB0_805
	s_and_b64 vcc, exec, s[6:7]
	s_cbranch_vccz .LBB0_808
	s_barrier
